# down-GEMM residual epilogue rewritten as 4-deep software pipeline (loads 4 blocks ahead, counted vmcnt), on top of up-hoist
# speedup vs baseline: 1.0075x; 1.0022x over previous
; __device__ __forceinline__ unsigned cvtpk(float lo, float hi) { f32x2 v = {lo, hi}; bf16x2_t b = __builtin_convertvector(v, bf16x2_t); return __builtin_bit_cast(unsigned, b); }
;     __device__ __forceinline__ void operator()(const f32x4 (&acc)[2][2][4][2], const pg8::Unit& u, int wr, int wc, int fr, int fq) const {
;     ...
;                 const int grow = row_base + u.pm * 256 + ai * 128 + wr * 64 + m * 16 + fr;
;                 const bool ok = grow < MREAL;
;                 float ss = 0.f;
;                 if (ok) {
;                     const float* src; float* dst;
;                     if (grow < ROWS_P) { src = srcA + (size_t)grow * DM; dst = dstMain + (size_t)grow * DM; }
;                     else if (grow < ROWS_MAIN) { src = srcB + (size_t)(grow - ROWS_P) * DM; dst = dstMain + (size_t)grow * DM; }
;                     else { const int mr = grow - ROWS_MAIN; src = srcM + (size_t)(mr & meta_mask) * DM; dst = dstM + (size_t)mr * DM; }
; #pragma unroll
;                     for (int bj = 0; bj < 2; ++bj) {
;                         const int col0 = u.pn * 256 + bj * 128 + wc * 32 + 8 * fq;
;                         const f32x4 h0 = *(const f32x4*)(src + col0) + acc[ai][bj][m][0];
;                         const f32x4 h1 = *(const f32x4*)(src + col0 + 4) + acc[ai][bj][m][1];
;                         *(f32x4*)(dst + col0) = h0; *(f32x4*)(dst + col0 + 4) = h1;
;                         if (P) { u32x4 w; w.x = cvtpk(h0[0], h0[1]); w.y = cvtpk(h0[2], h0[3]); w.z = cvtpk(h1[0], h1[1]); w.w = cvtpk(h1[2], h1[3]);
;                             *(u32x4*)(P + (size_t)grow * DM + col0) = w; }
;                         ss += (h0[0] * h0[0] + h0[1] * h0[1]) + (h0[2] * h0[2] + h0[3] * h0[3]) + (h1[0] * h1[0] + h1[1] * h1[1]) + (h1[2] * h1[2] + h1[3] * h1[3]);
;                     }
;                 }
;                 ss += __shfl_xor(ss, 16); ss += __shfl_xor(ss, 32);
;                 if (ok && fq == 0 && rowss_next) atomicAdd(rowss_next + grow, (u64)(ss * SS_SCALE));
.LBB0_2135:
	s_lshl_b32 vcc_lo, s8, 8
	s_add_i32 vcc_lo, vcc_lo, s66
	s_cmp_lt_u32 vcc_lo, 0x18000
	s_cbranch_scc0 .Lepi_old_dn
	s_cmp_lg_u64 s[18:19], 0
	s_cbranch_scc0 .Lepi_old_dn
	s_cmp_eq_u64 s[16:17], 0
	s_cbranch_scc0 .Lepi_old_dn
	s_lshl_b32 vcc_hi, s6, 10
	s_lshl_b32 s8, vcc_lo, 3
	s_add_u32 s8, s34, s8
	s_addc_u32 s9, s35, 0
	s_lshl_b32 s6, vcc_lo, 12
	s_add_u32 vcc_hi, vcc_hi, s6
	s_add_u32 s50, s12, vcc_hi
	s_addc_u32 s51, s13, 0
	s_lshr_b32 s6, vcc_hi, 1
	s_add_u32 s6, s30, s6
	s_addc_u32 s7, s31, 0
	s_cmp_lt_u32 vcc_lo, 0x8000
	s_cselect_b32 s48, s12, s36
	s_cselect_b32 s49, s13, s37
	s_cselect_b32 vcc_lo, 0, 0x8000000
	s_sub_u32 vcc_hi, vcc_hi, vcc_lo
	s_add_u32 s48, s48, vcc_hi
	s_addc_u32 s49, s49, 0
	v_lshlrev_b32_e32 v150, 12, v164
	v_lshl_add_u32 v150, v166, 2, v150
	v_lshrrev_b32_e32 v151, 1, v150
	v_lshlrev_b32_e32 v162, 3, v164
	global_load_dwordx4 v[168:171], v150, s[48:49]
	global_load_dwordx4 v[172:175], v150, s[48:49] offset:16
	global_load_dwordx4 v[176:179], v150, s[48:49] offset:512
	global_load_dwordx4 v[180:183], v150, s[48:49] offset:528
	s_add_u32 s48, s48, 0x10000
	s_addc_u32 s49, s49, 0
	global_load_dwordx4 v[184:187], v150, s[48:49]
	global_load_dwordx4 v[188:191], v150, s[48:49] offset:16
	global_load_dwordx4 v[192:195], v150, s[48:49] offset:512
	global_load_dwordx4 v[196:199], v150, s[48:49] offset:528
	s_add_u32 s48, s48, 0x10000
	s_addc_u32 s49, s49, 0
	global_load_dwordx4 v[216:219], v150, s[48:49]
	global_load_dwordx4 v[220:223], v150, s[48:49] offset:16
	global_load_dwordx4 v[224:227], v150, s[48:49] offset:512
	global_load_dwordx4 v[228:231], v150, s[48:49] offset:528
	s_add_u32 s48, s48, 0x10000
	s_addc_u32 s49, s49, 0
	global_load_dwordx4 v[142:145], v150, s[48:49]
	global_load_dwordx4 v[146:149], v150, s[48:49] offset:16
	global_load_dwordx4 v[158:161], v150, s[48:49] offset:512
	global_load_dwordx4 v[204:207], v150, s[48:49] offset:528
	s_add_u32 s48, s48, 0x50000
	s_addc_u32 s49, s49, 0
	s_waitcnt vmcnt(12)
	v_pk_add_f32 v[126:127], v[126:127], v[168:169]
	v_pk_add_f32 v[128:129], v[128:129], v[170:171]
	v_pk_add_f32 v[122:123], v[122:123], v[172:173]
	v_pk_add_f32 v[124:125], v[124:125], v[174:175]
	v_pk_add_f32 v[118:119], v[118:119], v[176:177]
	v_pk_add_f32 v[120:121], v[120:121], v[178:179]
	v_pk_add_f32 v[114:115], v[114:115], v[180:181]
	v_pk_add_f32 v[116:117], v[116:117], v[182:183]
	global_store_dwordx4 v150, v[126:129], s[50:51]
	global_store_dwordx4 v150, v[122:125], s[50:51] offset:16
	global_store_dwordx4 v150, v[118:121], s[50:51] offset:512
	global_store_dwordx4 v150, v[114:117], s[50:51] offset:528
	v_cvt_pk_bf16_f32 v168, v126, v127
	v_cvt_pk_bf16_f32 v169, v128, v129
	v_cvt_pk_bf16_f32 v170, v122, v123
	v_cvt_pk_bf16_f32 v171, v124, v125
	v_cvt_pk_bf16_f32 v172, v118, v119
	v_cvt_pk_bf16_f32 v173, v120, v121
	v_cvt_pk_bf16_f32 v174, v114, v115
	v_cvt_pk_bf16_f32 v175, v116, v117
	global_store_dwordx4 v151, v[168:171], s[6:7]
	global_store_dwordx4 v151, v[172:175], s[6:7] offset:256
	v_mul_f32_e32 v163, v126, v126
	v_mul_f32_e32 v200, v127, v127
	v_fmac_f32_e32 v163, v128, v128
	v_fmac_f32_e32 v200, v129, v129
	v_fmac_f32_e32 v163, v122, v122
	v_fmac_f32_e32 v200, v123, v123
	v_fmac_f32_e32 v163, v124, v124
	v_fmac_f32_e32 v200, v125, v125
	v_fmac_f32_e32 v163, v118, v118
	v_fmac_f32_e32 v200, v119, v119
	v_fmac_f32_e32 v163, v120, v120
	v_fmac_f32_e32 v200, v121, v121
	v_fmac_f32_e32 v163, v114, v114
	v_fmac_f32_e32 v200, v115, v115
	v_fmac_f32_e32 v163, v116, v116
	v_fmac_f32_e32 v200, v117, v117
	v_add_f32_e32 v114, v163, v200
	s_add_u32 s50, s50, 0x10000
	s_addc_u32 s51, s51, 0
	s_add_u32 s6, s6, 0x8000
	s_addc_u32 s7, s7, 0
	global_load_dwordx4 v[168:171], v150, s[48:49]
	global_load_dwordx4 v[172:175], v150, s[48:49] offset:16
	global_load_dwordx4 v[176:179], v150, s[48:49] offset:512
	global_load_dwordx4 v[180:183], v150, s[48:49] offset:528
	s_add_u32 s48, s48, 0x10000
	s_addc_u32 s49, s49, 0
	s_waitcnt vmcnt(18)
	v_pk_add_f32 v[110:111], v[110:111], v[184:185]
	v_pk_add_f32 v[112:113], v[112:113], v[186:187]
	v_pk_add_f32 v[106:107], v[106:107], v[188:189]
	v_pk_add_f32 v[108:109], v[108:109], v[190:191]
	v_pk_add_f32 v[102:103], v[102:103], v[192:193]
	v_pk_add_f32 v[104:105], v[104:105], v[194:195]
	v_pk_add_f32 v[98:99], v[98:99], v[196:197]
	v_pk_add_f32 v[100:101], v[100:101], v[198:199]
	global_store_dwordx4 v150, v[110:113], s[50:51]
	global_store_dwordx4 v150, v[106:109], s[50:51] offset:16
	global_store_dwordx4 v150, v[102:105], s[50:51] offset:512
	global_store_dwordx4 v150, v[98:101], s[50:51] offset:528
	v_cvt_pk_bf16_f32 v184, v110, v111
	v_cvt_pk_bf16_f32 v185, v112, v113
	v_cvt_pk_bf16_f32 v186, v106, v107
	v_cvt_pk_bf16_f32 v187, v108, v109
	v_cvt_pk_bf16_f32 v188, v102, v103
	v_cvt_pk_bf16_f32 v189, v104, v105
	v_cvt_pk_bf16_f32 v190, v98, v99
	v_cvt_pk_bf16_f32 v191, v100, v101
	global_store_dwordx4 v151, v[184:187], s[6:7]
	global_store_dwordx4 v151, v[188:191], s[6:7] offset:256
	v_mul_f32_e32 v163, v110, v110
	v_mul_f32_e32 v200, v111, v111
	v_fmac_f32_e32 v163, v112, v112
	v_fmac_f32_e32 v200, v113, v113
	v_fmac_f32_e32 v163, v106, v106
	v_fmac_f32_e32 v200, v107, v107
	v_fmac_f32_e32 v163, v108, v108
	v_fmac_f32_e32 v200, v109, v109
	v_fmac_f32_e32 v163, v102, v102
	v_fmac_f32_e32 v200, v103, v103
	v_fmac_f32_e32 v163, v104, v104
	v_fmac_f32_e32 v200, v105, v105
	v_fmac_f32_e32 v163, v98, v98
	v_fmac_f32_e32 v200, v99, v99
	v_fmac_f32_e32 v163, v100, v100
	v_fmac_f32_e32 v200, v101, v101
	v_add_f32_e32 v98, v163, v200
	s_add_u32 s50, s50, 0x10000
	s_addc_u32 s51, s51, 0
	s_add_u32 s6, s6, 0x8000
	s_addc_u32 s7, s7, 0
	global_load_dwordx4 v[184:187], v150, s[48:49]
	global_load_dwordx4 v[188:191], v150, s[48:49] offset:16
	global_load_dwordx4 v[192:195], v150, s[48:49] offset:512
	global_load_dwordx4 v[196:199], v150, s[48:49] offset:528
	s_add_u32 s48, s48, 0x10000
	s_addc_u32 s49, s49, 0
	s_waitcnt vmcnt(24)
; __device__ __forceinline__ unsigned cvtpk(float lo, float hi) { f32x2 v = {lo, hi}; bf16x2_t b = __builtin_convertvector(v, bf16x2_t); return __builtin_bit_cast(unsigned, b); }
;     __device__ __forceinline__ void operator()(const f32x4 (&acc)[2][2][4][2], const pg8::Unit& u, int wr, int wc, int fr, int fq) const {
;     ...
;                 const int grow = row_base + u.pm * 256 + ai * 128 + wr * 64 + m * 16 + fr;
;                 const bool ok = grow < MREAL;
;                 float ss = 0.f;
;                 if (ok) {
;                     const float* src; float* dst;
;                     if (grow < ROWS_P) { src = srcA + (size_t)grow * DM; dst = dstMain + (size_t)grow * DM; }
;                     else if (grow < ROWS_MAIN) { src = srcB + (size_t)(grow - ROWS_P) * DM; dst = dstMain + (size_t)grow * DM; }
;                     else { const int mr = grow - ROWS_MAIN; src = srcM + (size_t)(mr & meta_mask) * DM; dst = dstM + (size_t)mr * DM; }
; #pragma unroll
;                     for (int bj = 0; bj < 2; ++bj) {
;                         const int col0 = u.pn * 256 + bj * 128 + wc * 32 + 8 * fq;
;                         const f32x4 h0 = *(const f32x4*)(src + col0) + acc[ai][bj][m][0];
;                         const f32x4 h1 = *(const f32x4*)(src + col0 + 4) + acc[ai][bj][m][1];
;                         *(f32x4*)(dst + col0) = h0; *(f32x4*)(dst + col0 + 4) = h1;
;                         if (P) { u32x4 w; w.x = cvtpk(h0[0], h0[1]); w.y = cvtpk(h0[2], h0[3]); w.z = cvtpk(h1[0], h1[1]); w.w = cvtpk(h1[2], h1[3]);
;                             *(u32x4*)(P + (size_t)grow * DM + col0) = w; }
;                         ss += (h0[0] * h0[0] + h0[1] * h0[1]) + (h0[2] * h0[2] + h0[3] * h0[3]) + (h1[0] * h1[0] + h1[1] * h1[1]) + (h1[2] * h1[2] + h1[3] * h1[3]);
;                     }
;                 }
;                 ss += __shfl_xor(ss, 16); ss += __shfl_xor(ss, 32);
;                 if (ok && fq == 0 && rowss_next) atomicAdd(rowss_next + grow, (u64)(ss * SS_SCALE));
	v_pk_add_f32 v[94:95], v[94:95], v[216:217]
	v_pk_add_f32 v[96:97], v[96:97], v[218:219]
	v_pk_add_f32 v[90:91], v[90:91], v[220:221]
	v_pk_add_f32 v[92:93], v[92:93], v[222:223]
	v_pk_add_f32 v[86:87], v[86:87], v[224:225]
	v_pk_add_f32 v[88:89], v[88:89], v[226:227]
	v_pk_add_f32 v[82:83], v[82:83], v[228:229]
	v_pk_add_f32 v[84:85], v[84:85], v[230:231]
	global_store_dwordx4 v150, v[94:97], s[50:51]
	global_store_dwordx4 v150, v[90:93], s[50:51] offset:16
	global_store_dwordx4 v150, v[86:89], s[50:51] offset:512
	global_store_dwordx4 v150, v[82:85], s[50:51] offset:528
	v_cvt_pk_bf16_f32 v216, v94, v95
	v_cvt_pk_bf16_f32 v217, v96, v97
	v_cvt_pk_bf16_f32 v218, v90, v91
	v_cvt_pk_bf16_f32 v219, v92, v93
	v_cvt_pk_bf16_f32 v220, v86, v87
	v_cvt_pk_bf16_f32 v221, v88, v89
	v_cvt_pk_bf16_f32 v222, v82, v83
	v_cvt_pk_bf16_f32 v223, v84, v85
	global_store_dwordx4 v151, v[216:219], s[6:7]
	global_store_dwordx4 v151, v[220:223], s[6:7] offset:256
	v_mul_f32_e32 v163, v94, v94
	v_mul_f32_e32 v200, v95, v95
	v_fmac_f32_e32 v163, v96, v96
	v_fmac_f32_e32 v200, v97, v97
	v_fmac_f32_e32 v163, v90, v90
	v_fmac_f32_e32 v200, v91, v91
	v_fmac_f32_e32 v163, v92, v92
	v_fmac_f32_e32 v200, v93, v93
	v_fmac_f32_e32 v163, v86, v86
	v_fmac_f32_e32 v200, v87, v87
	v_fmac_f32_e32 v163, v88, v88
	v_fmac_f32_e32 v200, v89, v89
	v_fmac_f32_e32 v163, v82, v82
	v_fmac_f32_e32 v200, v83, v83
	v_fmac_f32_e32 v163, v84, v84
	v_fmac_f32_e32 v200, v85, v85
	v_add_f32_e32 v82, v163, v200
	s_add_u32 s50, s50, 0x10000
	s_addc_u32 s51, s51, 0
	s_add_u32 s6, s6, 0x8000
	s_addc_u32 s7, s7, 0
	global_load_dwordx4 v[216:219], v150, s[48:49]
	global_load_dwordx4 v[220:223], v150, s[48:49] offset:16
	global_load_dwordx4 v[224:227], v150, s[48:49] offset:512
	global_load_dwordx4 v[228:231], v150, s[48:49] offset:528
	s_add_u32 s48, s48, 0x10000
	s_addc_u32 s49, s49, 0
	s_waitcnt vmcnt(30)
	v_pk_add_f32 v[78:79], v[78:79], v[142:143]
	v_pk_add_f32 v[80:81], v[80:81], v[144:145]
	v_pk_add_f32 v[74:75], v[74:75], v[146:147]
	v_pk_add_f32 v[76:77], v[76:77], v[148:149]
	v_pk_add_f32 v[70:71], v[70:71], v[158:159]
	v_pk_add_f32 v[72:73], v[72:73], v[160:161]
	v_pk_add_f32 v[66:67], v[66:67], v[204:205]
	v_pk_add_f32 v[68:69], v[68:69], v[206:207]
	global_store_dwordx4 v150, v[78:81], s[50:51]
	global_store_dwordx4 v150, v[74:77], s[50:51] offset:16
	global_store_dwordx4 v150, v[70:73], s[50:51] offset:512
	global_store_dwordx4 v150, v[66:69], s[50:51] offset:528
	v_cvt_pk_bf16_f32 v142, v78, v79
	v_cvt_pk_bf16_f32 v143, v80, v81
	v_cvt_pk_bf16_f32 v144, v74, v75
	v_cvt_pk_bf16_f32 v145, v76, v77
	v_cvt_pk_bf16_f32 v146, v70, v71
	v_cvt_pk_bf16_f32 v147, v72, v73
	v_cvt_pk_bf16_f32 v148, v66, v67
	v_cvt_pk_bf16_f32 v149, v68, v69
	global_store_dwordx4 v151, v[142:145], s[6:7]
	global_store_dwordx4 v151, v[146:149], s[6:7] offset:256
	v_mul_f32_e32 v163, v78, v78
	v_mul_f32_e32 v200, v79, v79
	v_fmac_f32_e32 v163, v80, v80
	v_fmac_f32_e32 v200, v81, v81
	v_fmac_f32_e32 v163, v74, v74
	v_fmac_f32_e32 v200, v75, v75
	v_fmac_f32_e32 v163, v76, v76
	v_fmac_f32_e32 v200, v77, v77
	v_fmac_f32_e32 v163, v70, v70
	v_fmac_f32_e32 v200, v71, v71
	v_fmac_f32_e32 v163, v72, v72
	v_fmac_f32_e32 v200, v73, v73
	v_fmac_f32_e32 v163, v66, v66
	v_fmac_f32_e32 v200, v67, v67
	v_fmac_f32_e32 v163, v68, v68
	v_fmac_f32_e32 v200, v69, v69
	v_add_f32_e32 v66, v163, v200
	s_add_u32 s50, s50, 0x50000
	s_addc_u32 s51, s51, 0
	s_add_u32 s6, s6, 0x28000
	s_addc_u32 s7, s7, 0
	global_load_dwordx4 v[142:145], v150, s[48:49]
	global_load_dwordx4 v[146:149], v150, s[48:49] offset:16
	global_load_dwordx4 v[158:161], v150, s[48:49] offset:512
	global_load_dwordx4 v[204:207], v150, s[48:49] offset:528
	s_waitcnt vmcnt(30)
	v_pk_add_f32 v[62:63], v[62:63], v[168:169]
	v_pk_add_f32 v[64:65], v[64:65], v[170:171]
	v_pk_add_f32 v[58:59], v[58:59], v[172:173]
	v_pk_add_f32 v[60:61], v[60:61], v[174:175]
	v_pk_add_f32 v[54:55], v[54:55], v[176:177]
	v_pk_add_f32 v[56:57], v[56:57], v[178:179]
	v_pk_add_f32 v[50:51], v[50:51], v[180:181]
	v_pk_add_f32 v[52:53], v[52:53], v[182:183]
	global_store_dwordx4 v150, v[62:65], s[50:51]
	global_store_dwordx4 v150, v[58:61], s[50:51] offset:16
	global_store_dwordx4 v150, v[54:57], s[50:51] offset:512
	global_store_dwordx4 v150, v[50:53], s[50:51] offset:528
	v_cvt_pk_bf16_f32 v168, v62, v63
	v_cvt_pk_bf16_f32 v169, v64, v65
	v_cvt_pk_bf16_f32 v170, v58, v59
	v_cvt_pk_bf16_f32 v171, v60, v61
	v_cvt_pk_bf16_f32 v172, v54, v55
	v_cvt_pk_bf16_f32 v173, v56, v57
	v_cvt_pk_bf16_f32 v174, v50, v51
	v_cvt_pk_bf16_f32 v175, v52, v53
	global_store_dwordx4 v151, v[168:171], s[6:7]
	global_store_dwordx4 v151, v[172:175], s[6:7] offset:256
	v_mul_f32_e32 v163, v62, v62
	v_mul_f32_e32 v200, v63, v63
	v_fmac_f32_e32 v163, v64, v64
	v_fmac_f32_e32 v200, v65, v65
	v_fmac_f32_e32 v163, v58, v58
	v_fmac_f32_e32 v200, v59, v59
	v_fmac_f32_e32 v163, v60, v60
	v_fmac_f32_e32 v200, v61, v61
	v_fmac_f32_e32 v163, v54, v54
	v_fmac_f32_e32 v200, v55, v55
	v_fmac_f32_e32 v163, v56, v56
	v_fmac_f32_e32 v200, v57, v57
	v_fmac_f32_e32 v163, v50, v50
	v_fmac_f32_e32 v200, v51, v51
	v_fmac_f32_e32 v163, v52, v52
	v_fmac_f32_e32 v200, v53, v53
	v_add_f32_e32 v50, v163, v200
	s_add_u32 s50, s50, 0x10000
	s_addc_u32 s51, s51, 0
	s_add_u32 s6, s6, 0x8000
	s_addc_u32 s7, s7, 0
	s_waitcnt vmcnt(26)
; __device__ __forceinline__ unsigned cvtpk(float lo, float hi) { f32x2 v = {lo, hi}; bf16x2_t b = __builtin_convertvector(v, bf16x2_t); return __builtin_bit_cast(unsigned, b); }
;     __device__ __forceinline__ void operator()(const f32x4 (&acc)[2][2][4][2], const pg8::Unit& u, int wr, int wc, int fr, int fq) const {
;     ...
;                 const int grow = row_base + u.pm * 256 + ai * 128 + wr * 64 + m * 16 + fr;
;                 const bool ok = grow < MREAL;
;                 float ss = 0.f;
;                 if (ok) {
;                     const float* src; float* dst;
;                     if (grow < ROWS_P) { src = srcA + (size_t)grow * DM; dst = dstMain + (size_t)grow * DM; }
;                     else if (grow < ROWS_MAIN) { src = srcB + (size_t)(grow - ROWS_P) * DM; dst = dstMain + (size_t)grow * DM; }
;                     else { const int mr = grow - ROWS_MAIN; src = srcM + (size_t)(mr & meta_mask) * DM; dst = dstM + (size_t)mr * DM; }
; #pragma unroll
;                     for (int bj = 0; bj < 2; ++bj) {
;                         const int col0 = u.pn * 256 + bj * 128 + wc * 32 + 8 * fq;
;                         const f32x4 h0 = *(const f32x4*)(src + col0) + acc[ai][bj][m][0];
;                         const f32x4 h1 = *(const f32x4*)(src + col0 + 4) + acc[ai][bj][m][1];
;                         *(f32x4*)(dst + col0) = h0; *(f32x4*)(dst + col0 + 4) = h1;
;                         if (P) { u32x4 w; w.x = cvtpk(h0[0], h0[1]); w.y = cvtpk(h0[2], h0[3]); w.z = cvtpk(h1[0], h1[1]); w.w = cvtpk(h1[2], h1[3]);
;                             *(u32x4*)(P + (size_t)grow * DM + col0) = w; }
;                         ss += (h0[0] * h0[0] + h0[1] * h0[1]) + (h0[2] * h0[2] + h0[3] * h0[3]) + (h1[0] * h1[0] + h1[1] * h1[1]) + (h1[2] * h1[2] + h1[3] * h1[3]);
;                     }
;                 }
;                 ss += __shfl_xor(ss, 16); ss += __shfl_xor(ss, 32);
;                 if (ok && fq == 0 && rowss_next) atomicAdd(rowss_next + grow, (u64)(ss * SS_SCALE));
	v_pk_add_f32 v[46:47], v[46:47], v[184:185]
	v_pk_add_f32 v[48:49], v[48:49], v[186:187]
	v_pk_add_f32 v[42:43], v[42:43], v[188:189]
	v_pk_add_f32 v[44:45], v[44:45], v[190:191]
	v_pk_add_f32 v[38:39], v[38:39], v[192:193]
	v_pk_add_f32 v[40:41], v[40:41], v[194:195]
	v_pk_add_f32 v[34:35], v[34:35], v[196:197]
	v_pk_add_f32 v[36:37], v[36:37], v[198:199]
	global_store_dwordx4 v150, v[46:49], s[50:51]
	global_store_dwordx4 v150, v[42:45], s[50:51] offset:16
	global_store_dwordx4 v150, v[38:41], s[50:51] offset:512
	global_store_dwordx4 v150, v[34:37], s[50:51] offset:528
	v_cvt_pk_bf16_f32 v184, v46, v47
	v_cvt_pk_bf16_f32 v185, v48, v49
	v_cvt_pk_bf16_f32 v186, v42, v43
	v_cvt_pk_bf16_f32 v187, v44, v45
	v_cvt_pk_bf16_f32 v188, v38, v39
	v_cvt_pk_bf16_f32 v189, v40, v41
	v_cvt_pk_bf16_f32 v190, v34, v35
	v_cvt_pk_bf16_f32 v191, v36, v37
	global_store_dwordx4 v151, v[184:187], s[6:7]
	global_store_dwordx4 v151, v[188:191], s[6:7] offset:256
	v_mul_f32_e32 v163, v46, v46
	v_mul_f32_e32 v200, v47, v47
	v_fmac_f32_e32 v163, v48, v48
	v_fmac_f32_e32 v200, v49, v49
	v_fmac_f32_e32 v163, v42, v42
	v_fmac_f32_e32 v200, v43, v43
	v_fmac_f32_e32 v163, v44, v44
	v_fmac_f32_e32 v200, v45, v45
	v_fmac_f32_e32 v163, v38, v38
	v_fmac_f32_e32 v200, v39, v39
	v_fmac_f32_e32 v163, v40, v40
	v_fmac_f32_e32 v200, v41, v41
	v_fmac_f32_e32 v163, v34, v34
	v_fmac_f32_e32 v200, v35, v35
	v_fmac_f32_e32 v163, v36, v36
	v_fmac_f32_e32 v200, v37, v37
	v_add_f32_e32 v34, v163, v200
	s_add_u32 s50, s50, 0x10000
	s_addc_u32 s51, s51, 0
	s_add_u32 s6, s6, 0x8000
	s_addc_u32 s7, s7, 0
	s_waitcnt vmcnt(22)
	v_pk_add_f32 v[28:29], v[28:29], v[216:217]
	v_pk_add_f32 v[30:31], v[30:31], v[218:219]
	v_pk_add_f32 v[24:25], v[24:25], v[220:221]
	v_pk_add_f32 v[26:27], v[26:27], v[222:223]
	v_pk_add_f32 v[20:21], v[20:21], v[224:225]
	v_pk_add_f32 v[22:23], v[22:23], v[226:227]
	v_pk_add_f32 v[16:17], v[16:17], v[228:229]
	v_pk_add_f32 v[18:19], v[18:19], v[230:231]
	global_store_dwordx4 v150, v[28:31], s[50:51]
	global_store_dwordx4 v150, v[24:27], s[50:51] offset:16
	global_store_dwordx4 v150, v[20:23], s[50:51] offset:512
	global_store_dwordx4 v150, v[16:19], s[50:51] offset:528
	v_cvt_pk_bf16_f32 v216, v28, v29
	v_cvt_pk_bf16_f32 v217, v30, v31
	v_cvt_pk_bf16_f32 v218, v24, v25
	v_cvt_pk_bf16_f32 v219, v26, v27
	v_cvt_pk_bf16_f32 v220, v20, v21
	v_cvt_pk_bf16_f32 v221, v22, v23
	v_cvt_pk_bf16_f32 v222, v16, v17
	v_cvt_pk_bf16_f32 v223, v18, v19
	global_store_dwordx4 v151, v[216:219], s[6:7]
	global_store_dwordx4 v151, v[220:223], s[6:7] offset:256
	v_mul_f32_e32 v163, v28, v28
	v_mul_f32_e32 v200, v29, v29
	v_fmac_f32_e32 v163, v30, v30
	v_fmac_f32_e32 v200, v31, v31
	v_fmac_f32_e32 v163, v24, v24
	v_fmac_f32_e32 v200, v25, v25
	v_fmac_f32_e32 v163, v26, v26
	v_fmac_f32_e32 v200, v27, v27
	v_fmac_f32_e32 v163, v20, v20
	v_fmac_f32_e32 v200, v21, v21
	v_fmac_f32_e32 v163, v22, v22
	v_fmac_f32_e32 v200, v23, v23
	v_fmac_f32_e32 v163, v16, v16
	v_fmac_f32_e32 v200, v17, v17
	v_fmac_f32_e32 v163, v18, v18
	v_fmac_f32_e32 v200, v19, v19
	v_add_f32_e32 v16, v163, v200
	s_add_u32 s50, s50, 0x10000
	s_addc_u32 s51, s51, 0
	s_add_u32 s6, s6, 0x8000
	s_addc_u32 s7, s7, 0
	s_waitcnt vmcnt(18)
;     __device__ __forceinline__ void operator()(const f32x4 (&acc)[2][2][4][2], const pg8::Unit& u, int wr, int wc, int fr, int fq) const {
;     ...
;                         ss += (h0[0] * h0[0] + h0[1] * h0[1]) + (h0[2] * h0[2] + h0[3] * h0[3]) + (h1[0] * h1[0] + h1[1] * h1[1]) + (h1[2] * h1[2] + h1[3] * h1[3]);
;                     }
;                 }
;                 ss += __shfl_xor(ss, 16); ss += __shfl_xor(ss, 32);
;                 if (ok && fq == 0 && rowss_next) atomicAdd(rowss_next + grow, (u64)(ss * SS_SCALE));
	v_pk_add_f32 v[12:13], v[12:13], v[142:143]
	v_pk_add_f32 v[14:15], v[14:15], v[144:145]
	v_pk_add_f32 v[8:9], v[8:9], v[146:147]
	v_pk_add_f32 v[10:11], v[10:11], v[148:149]
	v_pk_add_f32 v[4:5], v[4:5], v[158:159]
	v_pk_add_f32 v[6:7], v[6:7], v[160:161]
	v_pk_add_f32 v[0:1], v[0:1], v[204:205]
	v_pk_add_f32 v[2:3], v[2:3], v[206:207]
	global_store_dwordx4 v150, v[12:15], s[50:51]
	global_store_dwordx4 v150, v[8:11], s[50:51] offset:16
	global_store_dwordx4 v150, v[4:7], s[50:51] offset:512
	global_store_dwordx4 v150, v[0:3], s[50:51] offset:528
	v_cvt_pk_bf16_f32 v142, v12, v13
	v_cvt_pk_bf16_f32 v143, v14, v15
	v_cvt_pk_bf16_f32 v144, v8, v9
	v_cvt_pk_bf16_f32 v145, v10, v11
	v_cvt_pk_bf16_f32 v146, v4, v5
	v_cvt_pk_bf16_f32 v147, v6, v7
	v_cvt_pk_bf16_f32 v148, v0, v1
	v_cvt_pk_bf16_f32 v149, v2, v3
	global_store_dwordx4 v151, v[142:145], s[6:7]
	global_store_dwordx4 v151, v[146:149], s[6:7] offset:256
	v_mul_f32_e32 v163, v12, v12
	v_mul_f32_e32 v200, v13, v13
	v_fmac_f32_e32 v163, v14, v14
	v_fmac_f32_e32 v200, v15, v15
	v_fmac_f32_e32 v163, v8, v8
	v_fmac_f32_e32 v200, v9, v9
	v_fmac_f32_e32 v163, v10, v10
	v_fmac_f32_e32 v200, v11, v11
	v_fmac_f32_e32 v163, v4, v4
	v_fmac_f32_e32 v200, v5, v5
	v_fmac_f32_e32 v163, v6, v6
	v_fmac_f32_e32 v200, v7, v7
	v_fmac_f32_e32 v163, v0, v0
	v_fmac_f32_e32 v200, v1, v1
	v_fmac_f32_e32 v163, v2, v2
	v_fmac_f32_e32 v200, v3, v3
	v_add_f32_e32 v0, v163, v200
	v_mbcnt_lo_u32_b32 v201, -1, 0
	v_mbcnt_hi_u32_b32 v201, -1, v201
	v_xor_b32_e32 v208, 16, v201
	v_xor_b32_e32 v209, 32, v201
	v_lshlrev_b32_e32 v208, 2, v208
	v_lshlrev_b32_e32 v209, 2, v209
	ds_bpermute_b32 v115, v208, v114
	ds_bpermute_b32 v99, v208, v98
	ds_bpermute_b32 v83, v208, v82
	ds_bpermute_b32 v67, v208, v66
	ds_bpermute_b32 v51, v208, v50
	ds_bpermute_b32 v35, v208, v34
	ds_bpermute_b32 v17, v208, v16
	ds_bpermute_b32 v1, v208, v0
	s_waitcnt lgkmcnt(0)
	v_add_f32_e32 v114, v114, v115
	v_add_f32_e32 v98, v98, v99
	v_add_f32_e32 v82, v82, v83
	v_add_f32_e32 v66, v66, v67
	v_add_f32_e32 v50, v50, v51
	v_add_f32_e32 v34, v34, v35
	v_add_f32_e32 v16, v16, v17
	v_add_f32_e32 v0, v0, v1
	ds_bpermute_b32 v115, v209, v114
	ds_bpermute_b32 v99, v209, v98
	ds_bpermute_b32 v83, v209, v82
	ds_bpermute_b32 v67, v209, v66
	ds_bpermute_b32 v51, v209, v50
	ds_bpermute_b32 v35, v209, v34
	ds_bpermute_b32 v17, v209, v16
	ds_bpermute_b32 v1, v209, v0
	s_waitcnt lgkmcnt(0)
	v_add_f32_e32 v114, v114, v115
	v_add_f32_e32 v98, v98, v99
	v_add_f32_e32 v82, v82, v83
	v_add_f32_e32 v66, v66, v67
	v_add_f32_e32 v50, v50, v51
	v_add_f32_e32 v34, v34, v35
	v_add_f32_e32 v16, v16, v17
	v_add_f32_e32 v0, v0, v1
	s_and_saveexec_b64 s[48:49], s[2:3]
	v_mul_f32_e32 v114, 0x49800000, v114
	v_trunc_f32_e32 v114, v114
	v_mul_f32_e32 v115, 0x2f800000, v114
	v_floor_f32_e32 v115, v115
	v_fmac_f32_e32 v114, 0xcf800000, v115
	v_cvt_u32_f32_e32 v116, v114
	v_cvt_u32_f32_e32 v117, v115
	global_atomic_add_x2 v162, v[116:117], s[8:9]
	v_mul_f32_e32 v98, 0x49800000, v98
	v_trunc_f32_e32 v98, v98
	v_mul_f32_e32 v99, 0x2f800000, v98
	v_floor_f32_e32 v99, v99
	v_fmac_f32_e32 v98, 0xcf800000, v99
	v_cvt_u32_f32_e32 v100, v98
	v_cvt_u32_f32_e32 v101, v99
	global_atomic_add_x2 v162, v[100:101], s[8:9] offset:128
	v_mul_f32_e32 v82, 0x49800000, v82
	v_trunc_f32_e32 v82, v82
	v_mul_f32_e32 v83, 0x2f800000, v82
	v_floor_f32_e32 v83, v83
	v_fmac_f32_e32 v82, 0xcf800000, v83
	v_cvt_u32_f32_e32 v84, v82
	v_cvt_u32_f32_e32 v85, v83
	global_atomic_add_x2 v162, v[84:85], s[8:9] offset:256
	v_mul_f32_e32 v66, 0x49800000, v66
	v_trunc_f32_e32 v66, v66
	v_mul_f32_e32 v67, 0x2f800000, v66
	v_floor_f32_e32 v67, v67
	v_fmac_f32_e32 v66, 0xcf800000, v67
	v_cvt_u32_f32_e32 v68, v66
	v_cvt_u32_f32_e32 v69, v67
	global_atomic_add_x2 v162, v[68:69], s[8:9] offset:384
	v_mul_f32_e32 v50, 0x49800000, v50
	v_trunc_f32_e32 v50, v50
	v_mul_f32_e32 v51, 0x2f800000, v50
	v_floor_f32_e32 v51, v51
	v_fmac_f32_e32 v50, 0xcf800000, v51
	v_cvt_u32_f32_e32 v52, v50
	v_cvt_u32_f32_e32 v53, v51
	global_atomic_add_x2 v162, v[52:53], s[8:9] offset:1024
	v_mul_f32_e32 v34, 0x49800000, v34
	v_trunc_f32_e32 v34, v34
	v_mul_f32_e32 v35, 0x2f800000, v34
	v_floor_f32_e32 v35, v35
	v_fmac_f32_e32 v34, 0xcf800000, v35
	v_cvt_u32_f32_e32 v36, v34
	v_cvt_u32_f32_e32 v37, v35
	global_atomic_add_x2 v162, v[36:37], s[8:9] offset:1152
	v_mul_f32_e32 v16, 0x49800000, v16
	v_trunc_f32_e32 v16, v16
	v_mul_f32_e32 v17, 0x2f800000, v16
	v_floor_f32_e32 v17, v17
	v_fmac_f32_e32 v16, 0xcf800000, v17
	v_cvt_u32_f32_e32 v18, v16
	v_cvt_u32_f32_e32 v19, v17
	global_atomic_add_x2 v162, v[18:19], s[8:9] offset:1280
	v_mul_f32_e32 v0, 0x49800000, v0
	v_trunc_f32_e32 v0, v0
	v_mul_f32_e32 v1, 0x2f800000, v0
	v_floor_f32_e32 v1, v1
	v_fmac_f32_e32 v0, 0xcf800000, v1
	v_cvt_u32_f32_e32 v2, v0
	v_cvt_u32_f32_e32 v3, v1
	global_atomic_add_x2 v162, v[2:3], s[8:9] offset:1408
	s_mov_b64 exec, s[48:49]
	s_branch .Lepi_done_dn

; #define PG8_BAR __builtin_amdgcn_s_barrier()
; template <class Epi, bool ALIGN_EPI = true>
; __device__ __forceinline__ void gemm_phase(PG8_LAS unsigned char* lds, const Gemm g, const StaticOrder& S, const Epi& E) {
;     ...
;         if (!has_next) break;
; #pragma unroll
;         for (int a = 0; a < 2; ++a)
; #pragma unroll
;             for (int b = 0; b < 2; ++b)
; #pragma unroll
;                 for (int m = 0; m < 4; ++m)
; #pragma unroll
;                     for (int n = 0; n < 2; ++n) acc[a][b][m][n] = (f32x4){0.f, 0.f, 0.f, 0.f};
;         cur = nxt; cA = nA; cB = nB; ++ui;
;         if constexpr (ALIGN_EPI) { if (wr == 1) PG8_BAR; }
.Lepi_done_dn:
	s_andn2_b64 vcc, exec, s[4:5]
	s_mov_b64 s[4:5], -1
	s_cbranch_vccnz .LBB0_2128
	s_andn2_b64 vcc, exec, s[28:29]
	s_cbranch_vccnz .LBB0_2127
	s_barrier
	s_branch .LBB0_2127
